# in-proj epilogue: rope tables prefetched two row groups ahead into dead fragment registers
# baseline (speedup 1.0000x reference)
;     __device__ __forceinline__ void operator()(const pg8::f32x4 (&acc)[2][2][4][2], const pg8::Unit& u, int wr, int wc, int fr, int fq) const {
;     ...
;                 const int row = row0 + ai * 128 + m * 16;
;                 const int tok = row & (SEQ - 1);
;                 bf16_t* rowp = base + (size_t)((row >> 13) * LP + PADF + NMETA + tok) * ldc + col0;
;                 const float scr = sc * rstd[row];
;                 f32x4 c0 = {1.f, 1.f, 1.f, 1.f}, c1 = c0, s0 = {0.f, 0.f, 0.f, 0.f}, s1 = s0;
;                 if (dorope) {
;                     const int pos = NMETA + tok;
;                     if (fq < 2) { c0 = *(const f32x4*)(ropec + pos * 8); c1 = *(const f32x4*)(ropec + pos * 8 + 4); s0 = *(const f32x4*)(ropes + pos * 8); s1 = *(const f32x4*)(ropes + pos * 8 + 4); }
.LBB0_335:
	v_lshl_add_u64 v[134:135], v[134:135], 2, s[72:73]
	global_load_dword v165, v[134:135], off
	global_load_dword v224, v[134:135], off offset:64
	global_load_dword v225, v[134:135], off offset:128
	global_load_dword v226, v[134:135], off offset:192
	global_load_dword v227, v[134:135], off offset:512
	global_load_dword v228, v[134:135], off offset:576
	global_load_dword v229, v[134:135], off offset:640
	global_load_dword v230, v[134:135], off offset:704
	s_and_b64 s[24:25], s[14:15], s[24:25]
	v_mov_b32_e32 v146, 0
	v_mov_b32_e32 v138, 1.0
	s_and_b64 s[30:31], s[24:25], s[42:43]
	v_and_b32_e32 v167, 0x1fcf, v166
	v_mov_b32_e32 v139, v138
	v_mov_b32_e32 v140, v138
	v_mov_b32_e32 v141, v138
	v_mov_b32_e32 v134, v138
	v_mov_b32_e32 v135, v138
	v_mov_b32_e32 v136, v138
	s_waitcnt lgkmcnt(0)
	v_mov_b32_e32 v137, v138
	v_mov_b32_e32 v147, v146
	v_mov_b32_e32 v148, v146
	v_mov_b32_e32 v149, v146
	v_mov_b32_e32 v142, v146
	v_mov_b32_e32 v143, v146
	v_mov_b32_e32 v144, v146
	v_mov_b32_e32 v145, v146
	s_and_saveexec_b64 s[28:29], s[30:31]
	s_cbranch_execz .LBB0_337
	v_readlane_b32 s22, v253, 20
	v_lshl_or_b32 v142, v167, 5, v220
	v_readlane_b32 s23, v253, 21
	v_lshl_or_b32 v208, v167, 5, v220
	v_add_u32_e32 v209, 0x1000, v208
	s_nop 4
	global_load_dwordx4 v[138:141], v142, s[22:23]
	global_load_dwordx4 v[134:137], v142, s[22:23] offset:16
	global_load_dwordx4 v[192:195], v208, s[22:23] offset:512
	global_load_dwordx4 v[196:199], v208, s[22:23] offset:528
	global_load_dwordx4 v[232:235], v208, s[22:23] offset:1024
	global_load_dwordx4 v[236:239], v208, s[22:23] offset:1040
	v_readlane_b32 s22, v253, 22
	v_readlane_b32 s23, v253, 23
	s_nop 4
	global_load_dwordx4 v[146:149], v142, s[22:23]
	s_nop 0
	global_load_dwordx4 v[142:145], v142, s[22:23] offset:16
	global_load_dwordx4 v[200:203], v208, s[22:23] offset:512
	global_load_dwordx4 v[204:207], v208, s[22:23] offset:528
	global_load_dwordx4 v[246:249], v208, s[22:23] offset:1024
	global_load_dwordx2 v[190:191], v208, s[22:23] offset:1040
	global_load_dwordx2 v[254:255], v208, s[22:23] offset:1048

;     __device__ __forceinline__ void operator()(const pg8::f32x4 (&acc)[2][2][4][2], const pg8::Unit& u, int wr, int wc, int fr, int fq) const {
;     ...
;                 const int row = row0 + ai * 128 + m * 16;
;                 const int tok = row & (SEQ - 1);
;                 bf16_t* rowp = base + (size_t)((row >> 13) * LP + PADF + NMETA + tok) * ldc + col0;
;                 const float scr = sc * rstd[row];
;                 f32x4 c0 = {1.f, 1.f, 1.f, 1.f}, c1 = c0, s0 = {0.f, 0.f, 0.f, 0.f}, s1 = s0;
;                 if (dorope) {
;                     const int pos = NMETA + tok;
;                     if (fq < 2) { c0 = *(const f32x4*)(ropec + pos * 8); c1 = *(const f32x4*)(ropec + pos * 8 + 4); s0 = *(const f32x4*)(ropes + pos * 8); s1 = *(const f32x4*)(ropes + pos * 8 + 4); }
.LBB0_345:
	v_cvt_pk_bf16_f32 v122, v122, v123
	v_cvt_pk_bf16_f32 v123, v124, v125
	v_cvt_pk_bf16_f32 v124, v118, v119
	v_or_b32_e32 v118, 16, v166
	v_cvt_pk_bf16_f32 v125, v120, v121
	v_ashrrev_i32_e32 v119, 31, v118
	global_store_dwordx4 v[126:127], v[122:125], off offset:256
	v_lshl_add_u64 v[118:119], v[118:119], 2, s[72:73]
	v_mov_b32_e32 v134, v224
	s_movk_i32 s0, 0x1fdf
	v_bitop3_b32 v138, v166, s0, 16 bitop3:0xc8
	v_mov_b32_e32 v130, 0
	v_mov_b32_e32 v122, 1.0
	v_mov_b32_e32 v123, 1.0
	v_mov_b32_e32 v124, 1.0
	v_mov_b32_e32 v125, 1.0
	v_mov_b32_e32 v118, 1.0
	v_mov_b32_e32 v119, 1.0
	v_mov_b32_e32 v120, 1.0
	v_mov_b32_e32 v121, 1.0
	v_mov_b32_e32 v131, 0
	v_mov_b32_e32 v132, 0
	v_mov_b32_e32 v133, 0
	v_mov_b32_e32 v126, 0
	v_mov_b32_e32 v127, 0
	v_mov_b32_e32 v128, 0
	v_mov_b32_e32 v129, 0
	s_and_saveexec_b64 s[20:21], s[30:31]
	s_cbranch_execz .LBB0_347
	v_mov_b32_e32 v122, v192
	v_mov_b32_e32 v123, v193
	v_mov_b32_e32 v124, v194
	v_mov_b32_e32 v125, v195
	v_mov_b32_e32 v118, v196
	v_mov_b32_e32 v119, v197
	v_mov_b32_e32 v120, v198
	v_mov_b32_e32 v121, v199
	v_mov_b32_e32 v130, v200
	v_mov_b32_e32 v131, v201
	v_mov_b32_e32 v132, v202
	v_mov_b32_e32 v133, v203
	v_mov_b32_e32 v126, v204
	v_mov_b32_e32 v127, v205
	v_mov_b32_e32 v128, v206
	v_mov_b32_e32 v129, v207
	v_readlane_b32 s0, v253, 20
	v_readlane_b32 s1, v253, 21
	s_nop 4
	global_load_dwordx4 v[192:195], v208, s[0:1] offset:1536
	global_load_dwordx4 v[196:199], v208, s[0:1] offset:1552
	v_readlane_b32 s0, v253, 22
	v_readlane_b32 s1, v253, 23
	s_nop 4
	global_load_dwordx4 v[200:203], v208, s[0:1] offset:1536
	global_load_dwordx4 v[204:207], v208, s[0:1] offset:1552

;     __device__ __forceinline__ void operator()(const pg8::f32x4 (&acc)[2][2][4][2], const pg8::Unit& u, int wr, int wc, int fr, int fq) const {
;     ...
;                 const int row = row0 + ai * 128 + m * 16;
;                 const int tok = row & (SEQ - 1);
;                 bf16_t* rowp = base + (size_t)((row >> 13) * LP + PADF + NMETA + tok) * ldc + col0;
;                 const float scr = sc * rstd[row];
;                 f32x4 c0 = {1.f, 1.f, 1.f, 1.f}, c1 = c0, s0 = {0.f, 0.f, 0.f, 0.f}, s1 = s0;
;                 if (dorope) {
;                     const int pos = NMETA + tok;
;                     if (fq < 2) { c0 = *(const f32x4*)(ropec + pos * 8); c1 = *(const f32x4*)(ropec + pos * 8 + 4); s0 = *(const f32x4*)(ropes + pos * 8); s1 = *(const f32x4*)(ropes + pos * 8 + 4); }
.LBB0_355:
	v_cvt_pk_bf16_f32 v106, v106, v107
	v_cvt_pk_bf16_f32 v107, v108, v109
	v_cvt_pk_bf16_f32 v108, v102, v103
	v_or_b32_e32 v102, 32, v166
	v_cvt_pk_bf16_f32 v109, v104, v105
	v_ashrrev_i32_e32 v103, 31, v102
	global_store_dwordx4 v[110:111], v[106:109], off offset:256
	v_lshl_add_u64 v[102:103], v[102:103], 2, s[72:73]
	v_mov_b32_e32 v118, v225
	s_movk_i32 s0, 0x1fef
	v_bitop3_b32 v122, v166, s0, 32 bitop3:0xc8
	v_mov_b32_e32 v114, 0
	v_mov_b32_e32 v106, 1.0
	v_mov_b32_e32 v107, 1.0
	v_mov_b32_e32 v108, 1.0
	v_mov_b32_e32 v109, 1.0
	v_mov_b32_e32 v102, 1.0
	v_mov_b32_e32 v103, 1.0
	v_mov_b32_e32 v104, 1.0
	v_mov_b32_e32 v105, 1.0
	v_mov_b32_e32 v115, 0
	v_mov_b32_e32 v116, 0
	v_mov_b32_e32 v117, 0
	v_mov_b32_e32 v110, 0
	v_mov_b32_e32 v111, 0
	v_mov_b32_e32 v112, 0
	v_mov_b32_e32 v113, 0
	s_and_saveexec_b64 s[20:21], s[30:31]
	s_cbranch_execz .LBB0_357
	v_mov_b32_e32 v106, v232
	v_mov_b32_e32 v107, v233
	v_mov_b32_e32 v108, v234
	v_mov_b32_e32 v109, v235
	v_mov_b32_e32 v102, v236
	v_mov_b32_e32 v103, v237
	v_mov_b32_e32 v104, v238
	v_mov_b32_e32 v105, v239
	v_mov_b32_e32 v114, v246
	v_mov_b32_e32 v115, v247
	v_mov_b32_e32 v116, v248
	v_mov_b32_e32 v117, v249
	v_mov_b32_e32 v110, v190
	v_mov_b32_e32 v111, v191
	v_mov_b32_e32 v112, v254
	v_mov_b32_e32 v113, v255
	v_readlane_b32 s0, v253, 20
	v_readlane_b32 s1, v253, 21
	s_nop 4
	global_load_dwordx4 v[232:235], v209, s[0:1]
	global_load_dwordx4 v[236:239], v209, s[0:1] offset:16
	v_readlane_b32 s0, v253, 22
	v_readlane_b32 s1, v253, 23
	s_nop 4
	global_load_dwordx4 v[246:249], v209, s[0:1]
	global_load_dwordx2 v[190:191], v209, s[0:1] offset:16
	global_load_dwordx2 v[254:255], v209, s[0:1] offset:24

;     __device__ __forceinline__ void operator()(const pg8::f32x4 (&acc)[2][2][4][2], const pg8::Unit& u, int wr, int wc, int fr, int fq) const {
;     ...
;                 const int row = row0 + ai * 128 + m * 16;
;                 const int tok = row & (SEQ - 1);
;                 bf16_t* rowp = base + (size_t)((row >> 13) * LP + PADF + NMETA + tok) * ldc + col0;
;                 const float scr = sc * rstd[row];
;                 f32x4 c0 = {1.f, 1.f, 1.f, 1.f}, c1 = c0, s0 = {0.f, 0.f, 0.f, 0.f}, s1 = s0;
;                 if (dorope) {
;                     const int pos = NMETA + tok;
;                     if (fq < 2) { c0 = *(const f32x4*)(ropec + pos * 8); c1 = *(const f32x4*)(ropec + pos * 8 + 4); s0 = *(const f32x4*)(ropes + pos * 8); s1 = *(const f32x4*)(ropes + pos * 8 + 4); }
.LBB0_365:
	v_cvt_pk_bf16_f32 v90, v90, v91
	v_cvt_pk_bf16_f32 v91, v92, v93
	v_cvt_pk_bf16_f32 v92, v86, v87
	v_or_b32_e32 v86, 48, v166
	v_cvt_pk_bf16_f32 v93, v88, v89
	v_ashrrev_i32_e32 v87, 31, v86
	global_store_dwordx4 v[94:95], v[90:93], off offset:256
	v_lshl_add_u64 v[86:87], v[86:87], 2, s[72:73]
	v_mov_b32_e32 v102, v226
	s_movk_i32 s0, 0x1fff
	v_bitop3_b32 v106, v166, s0, 48 bitop3:0xc8
	v_mov_b32_e32 v98, 0
	v_mov_b32_e32 v90, 1.0
	v_mov_b32_e32 v91, 1.0
	v_mov_b32_e32 v92, 1.0
	v_mov_b32_e32 v93, 1.0
	v_mov_b32_e32 v86, 1.0
	v_mov_b32_e32 v87, 1.0
	v_mov_b32_e32 v88, 1.0
	v_mov_b32_e32 v89, 1.0
	v_mov_b32_e32 v99, 0
	v_mov_b32_e32 v100, 0
	v_mov_b32_e32 v101, 0
	v_mov_b32_e32 v94, 0
	v_mov_b32_e32 v95, 0
	v_mov_b32_e32 v96, 0
	v_mov_b32_e32 v97, 0
	s_and_saveexec_b64 s[20:21], s[30:31]
	s_cbranch_execz .LBB0_367
	s_waitcnt vmcnt(9)
	v_mov_b32_e32 v90, v192
	v_mov_b32_e32 v91, v193
	v_mov_b32_e32 v92, v194
	v_mov_b32_e32 v93, v195
	v_mov_b32_e32 v86, v196
	v_mov_b32_e32 v87, v197
	v_mov_b32_e32 v88, v198
	v_mov_b32_e32 v89, v199
	v_mov_b32_e32 v98, v200
	v_mov_b32_e32 v99, v201
	v_mov_b32_e32 v100, v202
	v_mov_b32_e32 v101, v203
	v_mov_b32_e32 v94, v204
	v_mov_b32_e32 v95, v205
	v_mov_b32_e32 v96, v206
	v_mov_b32_e32 v97, v207
	v_readlane_b32 s0, v253, 20
	v_readlane_b32 s1, v253, 21
	s_nop 4
	global_load_dwordx4 v[192:195], v209, s[0:1] offset:512
	global_load_dwordx4 v[196:199], v209, s[0:1] offset:528
	v_readlane_b32 s0, v253, 22
	v_readlane_b32 s1, v253, 23
	s_nop 4
	global_load_dwordx4 v[200:203], v209, s[0:1] offset:512
	global_load_dwordx4 v[204:207], v209, s[0:1] offset:528

;     __device__ __forceinline__ void operator()(const pg8::f32x4 (&acc)[2][2][4][2], const pg8::Unit& u, int wr, int wc, int fr, int fq) const {
;     ...
;                 const int row = row0 + ai * 128 + m * 16;
;                 const int tok = row & (SEQ - 1);
;                 bf16_t* rowp = base + (size_t)((row >> 13) * LP + PADF + NMETA + tok) * ldc + col0;
;                 const float scr = sc * rstd[row];
;                 f32x4 c0 = {1.f, 1.f, 1.f, 1.f}, c1 = c0, s0 = {0.f, 0.f, 0.f, 0.f}, s1 = s0;
;                 if (dorope) {
;                     const int pos = NMETA + tok;
;                     if (fq < 2) { c0 = *(const f32x4*)(ropec + pos * 8); c1 = *(const f32x4*)(ropec + pos * 8 + 4); s0 = *(const f32x4*)(ropes + pos * 8); s1 = *(const f32x4*)(ropes + pos * 8 + 4); }
.LBB0_375:
	v_add_u32_e32 v86, 0x80, v166
	v_cvt_pk_bf16_f32 v74, v74, v75
	v_cvt_pk_bf16_f32 v75, v76, v77
	v_cvt_pk_bf16_f32 v76, v70, v71
	v_cvt_pk_bf16_f32 v77, v72, v73
	v_ashrrev_i32_e32 v87, 31, v86
	global_store_dwordx4 v[78:79], v[74:77], off offset:256
	v_lshl_add_u64 v[70:71], v[86:87], 2, s[72:73]
	v_mov_b32_e32 v88, v227
	v_and_b32_e32 v87, 0x1fcf, v86
	v_mov_b32_e32 v82, 0
	v_mov_b32_e32 v74, 1.0
	v_mov_b32_e32 v75, 1.0
	v_mov_b32_e32 v76, 1.0
	v_mov_b32_e32 v77, 1.0
	v_mov_b32_e32 v70, 1.0
	v_mov_b32_e32 v71, 1.0
	v_mov_b32_e32 v72, 1.0
	v_mov_b32_e32 v73, 1.0
	v_mov_b32_e32 v83, 0
	v_mov_b32_e32 v84, 0
	v_mov_b32_e32 v85, 0
	v_mov_b32_e32 v78, 0
	v_mov_b32_e32 v79, 0
	v_mov_b32_e32 v80, 0
	v_mov_b32_e32 v81, 0
	s_and_saveexec_b64 s[20:21], s[30:31]
	s_cbranch_execz .LBB0_377
	s_waitcnt vmcnt(8)
	v_mov_b32_e32 v74, v232
	v_mov_b32_e32 v75, v233
	v_mov_b32_e32 v76, v234
	v_mov_b32_e32 v77, v235
	v_mov_b32_e32 v70, v236
	v_mov_b32_e32 v71, v237
	v_mov_b32_e32 v72, v238
	v_mov_b32_e32 v73, v239
	v_mov_b32_e32 v82, v246
	v_mov_b32_e32 v83, v247
	v_mov_b32_e32 v84, v248
	v_mov_b32_e32 v85, v249
	v_mov_b32_e32 v78, v190
	v_mov_b32_e32 v79, v191
	v_mov_b32_e32 v80, v254
	v_mov_b32_e32 v81, v255
	v_readlane_b32 s0, v253, 20
	v_readlane_b32 s1, v253, 21
	s_nop 4
	global_load_dwordx4 v[232:235], v209, s[0:1] offset:1024
	global_load_dwordx4 v[236:239], v209, s[0:1] offset:1040
	v_readlane_b32 s0, v253, 22
	v_readlane_b32 s1, v253, 23
	s_nop 4
	global_load_dwordx4 v[246:249], v209, s[0:1] offset:1024
	global_load_dwordx2 v[190:191], v209, s[0:1] offset:1040
	global_load_dwordx2 v[254:255], v209, s[0:1] offset:1048

;     __device__ __forceinline__ void operator()(const pg8::f32x4 (&acc)[2][2][4][2], const pg8::Unit& u, int wr, int wc, int fr, int fq) const {
;     ...
;                 const int row = row0 + ai * 128 + m * 16;
;                 const int tok = row & (SEQ - 1);
;                 bf16_t* rowp = base + (size_t)((row >> 13) * LP + PADF + NMETA + tok) * ldc + col0;
;                 const float scr = sc * rstd[row];
;                 f32x4 c0 = {1.f, 1.f, 1.f, 1.f}, c1 = c0, s0 = {0.f, 0.f, 0.f, 0.f}, s1 = s0;
;                 if (dorope) {
;                     const int pos = NMETA + tok;
;                     if (fq < 2) { c0 = *(const f32x4*)(ropec + pos * 8); c1 = *(const f32x4*)(ropec + pos * 8 + 4); s0 = *(const f32x4*)(ropes + pos * 8); s1 = *(const f32x4*)(ropes + pos * 8 + 4); }
.LBB0_385:
	v_cvt_pk_bf16_f32 v58, v58, v59
	v_cvt_pk_bf16_f32 v59, v60, v61
	v_cvt_pk_bf16_f32 v60, v54, v55
	v_add_u32_e32 v54, 0x90, v166
	v_cvt_pk_bf16_f32 v61, v56, v57
	v_ashrrev_i32_e32 v55, 31, v54
	global_store_dwordx4 v[62:63], v[58:61], off offset:256
	v_lshl_add_u64 v[56:57], v[54:55], 2, s[72:73]
	v_mov_b32_e32 v70, v228
	v_and_b32_e32 v74, 0x1fdf, v54
	v_mov_b32_e32 v66, 0
	v_mov_b32_e32 v58, 1.0
	v_mov_b32_e32 v59, 1.0
	v_mov_b32_e32 v60, 1.0
	v_mov_b32_e32 v61, 1.0
	v_mov_b32_e32 v54, 1.0
	v_mov_b32_e32 v55, 1.0
	v_mov_b32_e32 v56, 1.0
	v_mov_b32_e32 v57, 1.0
	v_mov_b32_e32 v67, 0
	v_mov_b32_e32 v68, 0
	v_mov_b32_e32 v69, 0
	v_mov_b32_e32 v62, 0
	v_mov_b32_e32 v63, 0
	v_mov_b32_e32 v64, 0
	v_mov_b32_e32 v65, 0
	s_and_saveexec_b64 s[20:21], s[30:31]
	s_cbranch_execz .LBB0_387
	s_waitcnt vmcnt(9)
	v_mov_b32_e32 v58, v192
	v_mov_b32_e32 v59, v193
	v_mov_b32_e32 v60, v194
	v_mov_b32_e32 v61, v195
	v_mov_b32_e32 v54, v196
	v_mov_b32_e32 v55, v197
	v_mov_b32_e32 v56, v198
	v_mov_b32_e32 v57, v199
	v_mov_b32_e32 v66, v200
	v_mov_b32_e32 v67, v201
	v_mov_b32_e32 v68, v202
	v_mov_b32_e32 v69, v203
	v_mov_b32_e32 v62, v204
	v_mov_b32_e32 v63, v205
	v_mov_b32_e32 v64, v206
	v_mov_b32_e32 v65, v207
	v_readlane_b32 s0, v253, 20
	v_readlane_b32 s1, v253, 21
	s_nop 4
	global_load_dwordx4 v[192:195], v209, s[0:1] offset:1536
	global_load_dwordx4 v[196:199], v209, s[0:1] offset:1552
	v_readlane_b32 s0, v253, 22
	v_readlane_b32 s1, v253, 23
	s_nop 4
	global_load_dwordx4 v[200:203], v209, s[0:1] offset:1536
	global_load_dwordx4 v[204:207], v209, s[0:1] offset:1552

;     __device__ __forceinline__ void operator()(const pg8::f32x4 (&acc)[2][2][4][2], const pg8::Unit& u, int wr, int wc, int fr, int fq) const {
;     ...
;                 const int row = row0 + ai * 128 + m * 16;
;                 const int tok = row & (SEQ - 1);
;                 bf16_t* rowp = base + (size_t)((row >> 13) * LP + PADF + NMETA + tok) * ldc + col0;
;                 const float scr = sc * rstd[row];
;                 f32x4 c0 = {1.f, 1.f, 1.f, 1.f}, c1 = c0, s0 = {0.f, 0.f, 0.f, 0.f}, s1 = s0;
;                 if (dorope) {
;                     const int pos = NMETA + tok;
;                     if (fq < 2) { c0 = *(const f32x4*)(ropec + pos * 8); c1 = *(const f32x4*)(ropec + pos * 8 + 4); s0 = *(const f32x4*)(ropes + pos * 8); s1 = *(const f32x4*)(ropes + pos * 8 + 4); }
.LBB0_395:
	v_cvt_pk_bf16_f32 v42, v42, v43
	v_cvt_pk_bf16_f32 v43, v44, v45
	v_cvt_pk_bf16_f32 v44, v38, v39
	v_add_u32_e32 v38, 0xa0, v166
	v_cvt_pk_bf16_f32 v45, v40, v41
	v_ashrrev_i32_e32 v39, 31, v38
	global_store_dwordx4 v[46:47], v[42:45], off offset:256
	v_lshl_add_u64 v[40:41], v[38:39], 2, s[72:73]
	v_mov_b32_e32 v54, v229
	v_and_b32_e32 v58, 0x1fef, v38
	v_mov_b32_e32 v50, 0
	v_mov_b32_e32 v42, 1.0
	v_mov_b32_e32 v43, 1.0
	v_mov_b32_e32 v44, 1.0
	v_mov_b32_e32 v45, 1.0
	v_mov_b32_e32 v38, 1.0
	v_mov_b32_e32 v39, 1.0
	v_mov_b32_e32 v40, 1.0
	v_mov_b32_e32 v41, 1.0
	v_mov_b32_e32 v51, 0
	v_mov_b32_e32 v52, 0
	v_mov_b32_e32 v53, 0
	v_mov_b32_e32 v46, 0
	v_mov_b32_e32 v47, 0
	v_mov_b32_e32 v48, 0
	v_mov_b32_e32 v49, 0
	s_and_saveexec_b64 s[20:21], s[30:31]
	s_cbranch_execz .LBB0_397
	s_waitcnt vmcnt(8)
	v_mov_b32_e32 v42, v232
	v_mov_b32_e32 v43, v233
	v_mov_b32_e32 v44, v234
	v_mov_b32_e32 v45, v235
	v_mov_b32_e32 v38, v236
	v_mov_b32_e32 v39, v237
	v_mov_b32_e32 v40, v238
	v_mov_b32_e32 v41, v239
	v_mov_b32_e32 v50, v246
	v_mov_b32_e32 v51, v247
	v_mov_b32_e32 v52, v248
	v_mov_b32_e32 v53, v249
	v_mov_b32_e32 v46, v190
	v_mov_b32_e32 v47, v191
	v_mov_b32_e32 v48, v254
	v_mov_b32_e32 v49, v255

;     __device__ __forceinline__ void operator()(const pg8::f32x4 (&acc)[2][2][4][2], const pg8::Unit& u, int wr, int wc, int fr, int fq) const {
;     ...
;                 const int row = row0 + ai * 128 + m * 16;
;                 const int tok = row & (SEQ - 1);
;                 bf16_t* rowp = base + (size_t)((row >> 13) * LP + PADF + NMETA + tok) * ldc + col0;
;                 const float scr = sc * rstd[row];
;                 f32x4 c0 = {1.f, 1.f, 1.f, 1.f}, c1 = c0, s0 = {0.f, 0.f, 0.f, 0.f}, s1 = s0;
;                 if (dorope) {
;                     const int pos = NMETA + tok;
;                     if (fq < 2) { c0 = *(const f32x4*)(ropec + pos * 8); c1 = *(const f32x4*)(ropec + pos * 8 + 4); s0 = *(const f32x4*)(ropes + pos * 8); s1 = *(const f32x4*)(ropes + pos * 8 + 4); }
.LBB0_405:
	v_cvt_pk_bf16_f32 v26, v26, v27
	v_cvt_pk_bf16_f32 v27, v28, v29
	v_cvt_pk_bf16_f32 v28, v22, v23
	v_add_u32_e32 v22, 0xb0, v166
	v_cvt_pk_bf16_f32 v29, v24, v25
	v_ashrrev_i32_e32 v23, 31, v22
	global_store_dwordx4 v[30:31], v[26:29], off offset:256
	v_lshl_add_u64 v[24:25], v[22:23], 2, s[72:73]
	v_mov_b32_e32 v38, v230
	v_and_b32_e32 v42, 0x1fff, v22
	v_mov_b32_e32 v34, 0
	v_mov_b32_e32 v26, 1.0
	v_mov_b32_e32 v27, 1.0
	v_mov_b32_e32 v28, 1.0
	v_mov_b32_e32 v29, 1.0
	v_mov_b32_e32 v22, 1.0
	v_mov_b32_e32 v23, 1.0
	v_mov_b32_e32 v24, 1.0
	v_mov_b32_e32 v25, 1.0
	v_mov_b32_e32 v35, 0
	v_mov_b32_e32 v36, 0
	v_mov_b32_e32 v37, 0
	v_mov_b32_e32 v30, 0
	v_mov_b32_e32 v31, 0
	v_mov_b32_e32 v32, 0
	v_mov_b32_e32 v33, 0
	s_and_saveexec_b64 s[20:21], s[30:31]
	s_cbranch_execz .LBB0_407
	s_waitcnt vmcnt(4)
	v_mov_b32_e32 v26, v192
	v_mov_b32_e32 v27, v193
	v_mov_b32_e32 v28, v194
	v_mov_b32_e32 v29, v195
	v_mov_b32_e32 v22, v196
	v_mov_b32_e32 v23, v197
	v_mov_b32_e32 v24, v198
	v_mov_b32_e32 v25, v199
	v_mov_b32_e32 v34, v200
	v_mov_b32_e32 v35, v201
	v_mov_b32_e32 v36, v202
	v_mov_b32_e32 v37, v203
	v_mov_b32_e32 v30, v204
	v_mov_b32_e32 v31, v205
	v_mov_b32_e32 v32, v206
	v_mov_b32_e32 v33, v207
